# attention loop on 16x16x32 MFMA (O transposed per-lane query, LDS layout conversion at unit exit)
# speedup vs baseline: 1.0648x; 1.0121x over previous
.LBB0_254:
	s_cmp_lt_i32 s59, 1
	s_cbranch_scc1 .LBB0_360
	s_add_u32 s3, s66, 0x20200000
	v_writelane_b32 v254, s90, 11
	s_addc_u32 s6, s67, 0
	s_ashr_i32 s0, s88, 4
	v_writelane_b32 v254, s91, 12
	s_and_b32 s0, s0, -2
	v_writelane_b32 v254, s0, 13
	v_writelane_b32 v254, s88, 14
	s_and_b32 s0, s88, 31
	v_writelane_b32 v254, s0, 15
	s_and_b32 s0, s87, 0xffffffc0
	v_mov_b32_e32 v0, 0x3e4ccccd
	v_writelane_b32 v254, s0, 16
	s_lshl_b32 s0, s0, 2
	v_add_f32_e32 v0, s1, v0
	s_add_i32 s96, s0, 0
	s_add_i32 s0, s89, -4
	s_lshl_b32 s1, s89, 7
	s_lshl_b32 s4, s89, 18
	s_bfe_u32 s7, s87, 0x20006
	s_lshl_b32 s9, s0, 17
	s_and_b32 s1, s1, 0xffffff00
	s_and_b32 s4, s4, 0x40000
	s_lshl_b32 s0, s0, 13
	s_lshr_b32 s8, s87, 8
	s_lshl_b32 s14, s7, 5
	s_add_i32 s96, s96, 0x20200
	s_add_i32 s10, s1, s4
	s_lshl_b32 s11, s89, 13
	s_add_i32 s12, s0, 0x8000
	s_cmpk_lt_u32 s87, 0x100
	s_cselect_b64 s[0:1], -1, 0
	s_and_b64 s[4:5], s[0:1], exec
	s_movk_i32 s5, 0x80
	v_writelane_b32 v254, s89, 17
	s_cselect_b32 s4, s11, s12
	s_cselect_b32 s11, 0x8000, s5
	s_mov_b32 s5, 0x10000
	v_writelane_b32 v254, s87, 18
	s_cselect_b32 s12, s5, 0x100
	s_mov_b32 s5, 0x18000
	s_cselect_b32 s20, 0xc0, 0
	s_cselect_b32 s16, s5, 0x180
	s_mov_b32 s5, 0x20000
	v_writelane_b32 v254, s20, 19
	s_cselect_b32 s20, 0x80, 0
	s_cselect_b32 s17, s5, 0x10000
	s_mov_b32 s5, 0x28000
	v_writelane_b32 v254, s20, 20
	s_cselect_b32 s20, 64, 0
	s_cselect_b32 s18, s5, 0x10080
	s_mov_b32 s5, 0x30000
	v_writelane_b32 v254, s20, 21
	s_cselect_b32 s19, s5, 0x10100
	s_mov_b32 s5, 0x38000
	s_cselect_b32 s63, s95, s6
	v_writelane_b32 v254, s94, 22
	s_cselect_b32 s5, s5, 0x10180
	s_cselect_b32 s93, s10, s9
	v_writelane_b32 v254, s95, 23
	s_cselect_b32 s62, s94, s3
	s_add_i32 s97, s4, 0
	s_lshl_b32 s4, s8, 14
	v_writelane_b32 v254, s4, 24
	s_lshl_b32 s4, s7, 15
	s_add_i32 s75, s97, 0x400
	s_add_i32 s68, s97, 0x800
	s_add_i32 s69, s97, 0xc00
	s_add_i32 s78, s97, 0x1000
	s_add_i32 s79, s97, 0x1400
	s_add_i32 s54, s97, 0x1800
	s_add_i32 s55, s97, 0x1c00
	s_lshl_b32 s3, s8, 7
	s_add_i32 s71, s97, 0x10000
	s_add_i32 s92, s97, 0x10400
	s_add_i32 s70, s97, 0x10800
	s_add_i32 s80, s97, 0x10c00
	s_add_i32 s81, s97, 0x11000
	s_add_i32 s50, s97, 0x11400
	s_add_i32 s51, s97, 0x11800
	s_add_i32 s94, s97, 0x11c00
	s_add_i32 s95, s4, 0
	s_cmp_eq_u32 s8, 1
	s_cselect_b64 s[6:7], -1, 0
	v_writelane_b32 v254, s6, 25
	s_lshl_b32 s4, s8, 4
	s_mov_b32 s15, 0
	v_writelane_b32 v254, s7, 26
	v_writelane_b32 v254, s4, 27
	v_writelane_b32 v254, s14, 28
	s_add_i32 s4, s14, 0xffffffa5
	v_writelane_b32 v254, s4, 29
	v_writelane_b32 v254, s5, 30
	s_add_i32 s4, s93, s5
	v_writelane_b32 v254, s4, 31
	v_writelane_b32 v254, s16, 32
	s_add_i32 s4, s93, s16
	v_writelane_b32 v254, s4, 33
	v_writelane_b32 v254, s19, 34
	s_add_i32 s4, s93, s19
	v_writelane_b32 v254, s4, 35
	v_writelane_b32 v254, s12, 36
	s_add_i32 s4, s93, s12
	v_writelane_b32 v254, s4, 37
	v_writelane_b32 v254, s18, 38
	s_add_i32 s4, s93, s18
	v_writelane_b32 v254, s4, 39
	v_writelane_b32 v254, s11, 40
	s_add_i32 s4, s93, s11
	v_writelane_b32 v254, s4, 41
	v_writelane_b32 v254, s17, 42
	s_add_i32 s4, s93, s17
	v_xor_b32_e32 v210, 0x80000000, v0
	v_writelane_b32 v254, s4, 43
	s_lshl_b32 s14, s3, 1
	v_mov_b32_e32 v212, v210
	v_mov_b32_e32 v213, v210
	v_mov_b32_e32 v1, 0
	s_mov_b32 s74, 0x41000000
	v_mov_b32_e32 v214, 0x3727c5ac
	v_mov_b32_e32 v215, 0x41b17218
	v_mov_b32_e32 v216, 0xff800000
	v_writelane_b32 v254, s14, 44
	s_mov_b32 s72, s15
	s_nop 0
	v_writelane_b32 v254, s15, 45
	s_branch .LBB0_257

.LBB0_265:
	s_or_b64 exec, exec, s[6:7]
	v_ashrrev_i32_e32 v0, 4, v211
	v_lshlrev_b32_e32 v2, 13, v0
	v_bitop3_b32 v3, v211, v0, 15 bitop3:0x6c
	v_ashrrev_i32_e32 v218, 5, v211
	v_lshl_add_u32 v2, v3, 4, v2
	v_lshlrev_b32_e32 v0, 3, v0
	v_bfe_u32 v3, v211, 2, 2
	s_and_b32 s5, s72, 1
	s_sub_i32 s6, 0x7f, s3
	v_and_or_b32 v0, v0, 8, v3
	v_lshlrev_b32_e32 v3, 6, v218
	s_cmp_eq_u32 s5, 0
	v_lshl_add_u32 v0, v0, 13, v3
	v_lshlrev_b32_e32 v6, 4, v211
	s_cselect_b32 s5, s6, s3
	v_and_or_b32 v0, v6, 48, v0
	s_lshl_b32 s90, s4, 9
	v_bfe_u32 v0, v211, 1, 3
	v_lshlrev_b32_e32 v0, 13, v0
	v_lshrrev_b32_e32 v3, 4, v211
	v_lshl_add_u32 v0, v3, 5, v0
	v_and_b32_e32 v3, 1, v211
	v_lshl_add_u32 v0, v3, 4, v0
	v_cndmask_b32_e64 v7, v0, v2, s[0:1]
	s_add_i32 s7, s90, s93
	v_add_u32_e32 v0, s7, v7
	s_mov_b32 s8, m0
	s_mov_b32 m0, s97
	s_nop 0
	global_load_lds_dwordx4 v0, s[62:63]
	s_mov_b32 m0, s8
	s_lshl_b32 s6, s5, 7
	v_readlane_b32 s8, v254, 21
	v_readlane_b32 s3, v254, 28
	v_and_b32_e32 v217, 31, v211
	v_xor_b32_e32 v8, s8, v7
	v_add_u32_e32 v2, s7, v8
	v_readlane_b32 s8, v254, 40
	s_or_b32 s3, s6, s3
	s_lshl_b32 s82, s4, 8
	v_add_u32_e32 v3, s8, v2
	s_mov_b32 s8, m0
	s_mov_b32 m0, s75
	s_nop 0
	global_load_lds_dwordx4 v3, s[62:63]
	s_mov_b32 m0, s8
	s_ashr_i32 s83, s82, 31
	v_readlane_b32 s8, v254, 20
	v_readlane_b32 s4, v254, 24
	v_mov_b32_e32 v14, v1
	v_xor_b32_e32 v9, s8, v7
	v_add_u32_e32 v3, s7, v9
	v_readlane_b32 s8, v254, 36
	v_mov_b32_e32 v15, v1
	v_add_u32_e32 v231, s93, v7
	v_add_u32_e32 v4, s8, v3
	s_mov_b32 s8, m0
	s_mov_b32 m0, s68
	s_nop 0
	global_load_lds_dwordx4 v4, s[62:63]
	s_mov_b32 m0, s8
	v_mov_b32_e32 v11, v1
	v_readlane_b32 s8, v254, 19
	v_mov_b32_e32 v12, v1
	v_mov_b32_e32 v13, v1
	v_xor_b32_e32 v10, s8, v7
	v_add_u32_e32 v4, s7, v10
	v_readlane_b32 s7, v254, 32
	v_readlane_b32 s8, v254, 44
	v_readlane_b32 s9, v254, 45
	v_add_u32_e32 v5, s7, v4
	s_mov_b32 s7, m0
	s_mov_b32 m0, s69
	s_nop 0
	global_load_lds_dwordx4 v5, s[62:63]
	s_mov_b32 m0, s7
	s_mov_b32 s91, 0
	v_readlane_b32 s7, v254, 42
	s_lshl_b32 s88, s5, 1
	s_lshr_b32 s89, s3, 6
	v_add_u32_e32 v0, s7, v0
	s_mov_b32 s7, m0
	s_mov_b32 m0, s78
	s_nop 0
	global_load_lds_dwordx4 v0, s[62:63]
	s_mov_b32 m0, s7
	s_add_i32 s73, s3, 0xffffff10
	v_readlane_b32 s7, v254, 38
	v_cmp_gt_u32_e64 s[36:37], 32, v211
	v_lshl_add_u32 v220, v217, 2, s96
	v_add_u32_e32 v0, s7, v2
	s_mov_b32 s7, m0
	s_mov_b32 m0, s79
	s_nop 0
	global_load_lds_dwordx4 v0, s[62:63]
	s_mov_b32 m0, s7
	v_lshlrev_b32_e32 v219, 4, v218
	v_readlane_b32 s7, v254, 34
	v_mov_b32_e32 v233, 0xf149f2ca
	v_mov_b32_e32 v232, 0
	v_add_u32_e32 v0, s7, v3
	s_mov_b32 s7, m0
	s_mov_b32 m0, s54
	s_nop 0
	global_load_lds_dwordx4 v0, s[62:63]
	s_mov_b32 m0, s7
	s_mov_b32 s58, 0
	v_readlane_b32 s7, v254, 30
	s_nop 1
	v_add_u32_e32 v0, s7, v4
	s_mov_b32 s7, m0
	s_mov_b32 m0, s55
	s_nop 0
	global_load_lds_dwordx4 v0, s[62:63]
	s_mov_b32 m0, s7
	v_and_b32_e32 v0, 15, v211
	v_or_b32_e32 v0, s3, v0
	v_lshlrev_b32_e32 v0, 13, v0
	v_lshl_add_u64 v[2:3], s[42:43], 0, v[0:1]
	v_lshl_add_u64 v[2:3], s[82:83], 1, v[2:3]
	v_lshrrev_b32_e32 v4, 4, v211
	v_lshlrev_b32_e32 v4, 3, v4
	v_lshl_add_u64 v[2:3], v[2:3], 0, s[8:9]
	v_ashrrev_i32_e32 v5, 31, v4
	v_lshl_add_u64 v[2:3], v[4:5], 1, v[2:3]
	s_mov_b32 s8, 0x20000
	s_mov_b32 s9, 0
	v_lshl_add_u64 v[4:5], v[2:3], 0, s[8:9]
	global_load_dwordx4 v[178:181], v[2:3], off
	global_load_dwordx4 v[182:185], v[2:3], off offset:64
	global_load_dwordx4 v[186:189], v[2:3], off offset:128
	global_load_dwordx4 v[190:193], v[2:3], off offset:192
	global_load_dwordx4 v[194:197], v[4:5], off
	global_load_dwordx4 v[198:201], v[4:5], off offset:64
	global_load_dwordx4 v[202:205], v[4:5], off offset:128
	global_load_dwordx4 v[206:209], v[4:5], off offset:192
	v_lshlrev_b32_e32 v2, 3, v211
	v_and_b32_e32 v3, 0xc0, v6
	v_lshlrev_b32_e32 v4, 1, v211
	v_and_or_b32 v3, v2, 24, v3
	v_and_b32_e32 v4, 32, v4
	v_and_b32_e32 v2, 0x100, v2
	v_or3_b32 v2, v3, v4, v2
	v_lshl_or_b32 v3, v217, 8, s4
	s_add_i32 s4, 0, 0x8000
	v_add_u32_e32 v222, s4, v2
	v_readlane_b32 s4, v254, 29
	s_add_i32 s4, s4, s6
	v_bitop3_b32 v0, v211, v218, 15 bitop3:0x6c
	v_add_u32_e32 v2, s4, v217
	v_readlane_b32 s4, v254, 31
	v_lshl_add_u32 v221, v0, 4, v3
	v_lshlrev_b32_e32 v0, 2, v218
	v_add_u32_e32 v224, s4, v10
	v_readlane_b32 s4, v254, 33
	v_sub_u32_e32 v223, v2, v0
	v_mov_b32_e32 v0, v1
	v_add_u32_e32 v225, s4, v10
	v_readlane_b32 s4, v254, 35
	v_mov_b32_e32 v2, v1
	v_mov_b32_e32 v3, v1
	v_add_u32_e32 v226, s4, v9
	v_readlane_b32 s4, v254, 37
	v_mov_b32_e32 v4, v1
	v_mov_b32_e32 v5, v1
	v_add_u32_e32 v227, s4, v9
	v_readlane_b32 s4, v254, 39
	v_mov_b32_e32 v6, v1
	v_mov_b32_e32 v9, v1
	v_add_u32_e32 v228, s4, v8
	v_readlane_b32 s4, v254, 41
	v_mov_b32_e32 v10, v1
	s_nop 0
	v_add_u32_e32 v229, s4, v8
	v_readlane_b32 s4, v254, 43
	v_mov_b32_e32 v8, v1
	s_nop 0
	v_add_u32_e32 v230, s4, v7
	v_mov_b32_e32 v7, v1
	v_mov_b64_e32 v[128:129], v[14:15]
	v_mov_b64_e32 v[112:113], v[14:15]
	v_mov_b64_e32 v[96:97], v[14:15]
	v_mov_b64_e32 v[80:81], v[14:15]
	v_mov_b64_e32 v[64:65], v[14:15]
	v_mov_b64_e32 v[48:49], v[14:15]
	v_mov_b64_e32 v[32:33], v[14:15]
	v_mov_b64_e32 v[126:127], v[12:13]
	v_mov_b64_e32 v[124:125], v[10:11]
	v_mov_b64_e32 v[122:123], v[8:9]
	v_mov_b64_e32 v[120:121], v[6:7]
	v_mov_b64_e32 v[118:119], v[4:5]
	v_mov_b64_e32 v[116:117], v[2:3]
	v_mov_b64_e32 v[114:115], v[0:1]
	v_mov_b64_e32 v[110:111], v[12:13]
	v_mov_b64_e32 v[108:109], v[10:11]
	v_mov_b64_e32 v[106:107], v[8:9]
	v_mov_b64_e32 v[104:105], v[6:7]
	v_mov_b64_e32 v[102:103], v[4:5]
	v_mov_b64_e32 v[100:101], v[2:3]
	v_mov_b64_e32 v[98:99], v[0:1]
	v_mov_b64_e32 v[94:95], v[12:13]
	v_mov_b64_e32 v[92:93], v[10:11]
	v_mov_b64_e32 v[90:91], v[8:9]
	v_mov_b64_e32 v[88:89], v[6:7]
	v_mov_b64_e32 v[86:87], v[4:5]
	v_mov_b64_e32 v[84:85], v[2:3]
	v_mov_b64_e32 v[82:83], v[0:1]
	v_mov_b64_e32 v[78:79], v[12:13]
	v_mov_b64_e32 v[76:77], v[10:11]
	v_mov_b64_e32 v[74:75], v[8:9]
	v_mov_b64_e32 v[72:73], v[6:7]
	v_mov_b64_e32 v[70:71], v[4:5]
	v_mov_b64_e32 v[68:69], v[2:3]
	v_mov_b64_e32 v[66:67], v[0:1]
	v_mov_b64_e32 v[62:63], v[12:13]
	v_mov_b64_e32 v[60:61], v[10:11]
	v_mov_b64_e32 v[58:59], v[8:9]
	v_mov_b64_e32 v[56:57], v[6:7]
	v_mov_b64_e32 v[54:55], v[4:5]
	v_mov_b64_e32 v[52:53], v[2:3]
	v_mov_b64_e32 v[50:51], v[0:1]
	v_mov_b64_e32 v[46:47], v[12:13]
	v_mov_b64_e32 v[44:45], v[10:11]
	v_mov_b64_e32 v[42:43], v[8:9]
	v_mov_b64_e32 v[40:41], v[6:7]
	v_mov_b64_e32 v[38:39], v[4:5]
	v_mov_b64_e32 v[36:37], v[2:3]
	v_mov_b64_e32 v[34:35], v[0:1]
	v_mov_b64_e32 v[30:31], v[12:13]
	v_mov_b64_e32 v[28:29], v[10:11]
	v_mov_b64_e32 v[26:27], v[8:9]
	v_mov_b64_e32 v[24:25], v[6:7]
	v_mov_b64_e32 v[22:23], v[4:5]
	v_mov_b64_e32 v[20:21], v[2:3]
	v_mov_b64_e32 v[18:19], v[0:1]
	v_mov_b64_e32 v[16:17], v[14:15]
	v_mov_b64_e32 v[14:15], v[12:13]
	v_mov_b64_e32 v[12:13], v[10:11]
	v_mov_b64_e32 v[10:11], v[8:9]
	v_mov_b64_e32 v[8:9], v[6:7]
	v_mov_b64_e32 v[6:7], v[4:5]
	v_mov_b64_e32 v[4:5], v[2:3]
	v_mov_b64_e32 v[2:3], v[0:1]
	s_branch .Lat_entry
.Lat_entry:
	s_mov_b32 s92, m0
	s_add_i32 s71, s97, 0x10000
	s_mov_b32 s70, 0
	s_movk_i32 s81, 0x7f
	s_mov_b32 s50, 0x20000
	s_add_i32 s51, s90, 0x80000
	v_add_u32_e32 v231, s51, v231
	v_add_u32_e32 v229, s51, v229
	v_add_u32_e32 v227, s51, v227
	v_add_u32_e32 v225, s51, v225
	v_add_u32_e32 v230, s51, v230
	v_add_u32_e32 v228, s51, v228
	v_add_u32_e32 v226, s51, v226
	v_add_u32_e32 v224, s51, v224
	v_readlane_b32 s4, v254, 24
	v_and_b32_e32 v234, 15, v211
	v_lshrrev_b32_e32 v235, 4, v211
	v_xor_b32_e32 v236, v234, v235
	v_lshlrev_b32_e32 v236, 4, v236
	v_lshl_add_u32 v236, v234, 8, v236
	v_add_u32_e32 v221, s4, v236
	v_lshlrev_b32_e32 v237, 2, v235
	v_sub_u32_e32 v237, v234, v237
	v_add_u32_e32 v223, s3, v237
	v_bfe_u32 v237, v211, 5, 1
	v_lshlrev_b32_e32 v237, 12, v237
	v_bfe_u32 v238, v211, 4, 1
	v_lshl_add_u32 v237, v238, 7, v237
	v_bfe_u32 v238, v211, 2, 2
	v_lshl_add_u32 v237, v238, 5, v237
	v_and_b32_e32 v238, 3, v211
	v_lshl_add_u32 v237, v238, 3, v237
	v_add_u32_e32 v222, 0x8000, v237
	v_mov_b32_e32 v243, v233
	v_mov_b32_e32 v244, 0
	v_xor_b32_e32 v234, s70, v221
	v_xor_b32_e32 v235, 64, v234
	v_xor_b32_e32 v236, 0x80, v234
	v_xor_b32_e32 v237, 0xc0, v234
.Lat_loop:
	s_waitcnt vmcnt(0) lgkmcnt(0)
	s_barrier
	s_cmp_gt_u32 s58, s89
	s_cbranch_scc1 .Lat_inactive
	ds_read_b128 v[162:165], v234
	ds_read_b128 v[166:169], v235
	ds_read_b128 v[170:173], v236
	ds_read_b128 v[174:177], v237
	v_add_u32_e32 v242, s70, v222
	s_add_i32 m0, s71, 0x0
	s_nop 0
	global_load_lds_dwordx4 v231, s[62:63]
	v_add_u32_e32 v231, 0x80000, v231
	s_add_i32 m0, s71, 0x400
	s_nop 0
	global_load_lds_dwordx4 v229, s[62:63]
	v_add_u32_e32 v229, 0x80000, v229
	s_waitcnt lgkmcnt(3)
	v_mfma_f32_16x16x32_bf16 v[130:133], v[162:165], v[178:181], 0
	v_mfma_f32_16x16x32_bf16 v[146:149], v[162:165], v[194:197], 0
	ds_read_b128 v[162:165], v234 offset:4096
	s_waitcnt lgkmcnt(3)
	v_mfma_f32_16x16x32_bf16 v[130:133], v[166:169], v[182:185], v[130:133]
	v_mfma_f32_16x16x32_bf16 v[146:149], v[166:169], v[198:201], v[146:149]
	ds_read_b128 v[166:169], v235 offset:4096
	s_add_i32 m0, s71, 0x800
	s_nop 0
	global_load_lds_dwordx4 v227, s[62:63]
	v_add_u32_e32 v227, 0x80000, v227
	s_waitcnt lgkmcnt(3)
	v_mfma_f32_16x16x32_bf16 v[130:133], v[170:173], v[186:189], v[130:133]
	v_mfma_f32_16x16x32_bf16 v[146:149], v[170:173], v[202:205], v[146:149]
	ds_read_b128 v[170:173], v236 offset:4096
	s_waitcnt lgkmcnt(3)
	v_mfma_f32_16x16x32_bf16 v[130:133], v[174:177], v[190:193], v[130:133]
	v_mfma_f32_16x16x32_bf16 v[146:149], v[174:177], v[206:209], v[146:149]
	ds_read_b128 v[174:177], v237 offset:4096
	s_add_i32 m0, s71, 0xc00
	s_nop 0
	global_load_lds_dwordx4 v225, s[62:63]
	v_add_u32_e32 v225, 0x80000, v225
	s_waitcnt lgkmcnt(3)
	v_mfma_f32_16x16x32_bf16 v[134:137], v[162:165], v[178:181], 0
	v_mfma_f32_16x16x32_bf16 v[150:153], v[162:165], v[194:197], 0
	ds_read_b128 v[162:165], v234 offset:8192
	s_waitcnt lgkmcnt(3)
	v_mfma_f32_16x16x32_bf16 v[134:137], v[166:169], v[182:185], v[134:137]
	v_mfma_f32_16x16x32_bf16 v[150:153], v[166:169], v[198:201], v[150:153]
	ds_read_b128 v[166:169], v235 offset:8192
	s_add_i32 m0, s71, 0x1000
	s_nop 0
	global_load_lds_dwordx4 v230, s[62:63]
	v_add_u32_e32 v230, 0x80000, v230
	s_waitcnt lgkmcnt(3)
	v_mfma_f32_16x16x32_bf16 v[134:137], v[170:173], v[186:189], v[134:137]
	v_mfma_f32_16x16x32_bf16 v[150:153], v[170:173], v[202:205], v[150:153]
	ds_read_b128 v[170:173], v236 offset:8192
	s_waitcnt lgkmcnt(3)
	v_mfma_f32_16x16x32_bf16 v[134:137], v[174:177], v[190:193], v[134:137]
	v_mfma_f32_16x16x32_bf16 v[150:153], v[174:177], v[206:209], v[150:153]
	ds_read_b128 v[174:177], v237 offset:8192
	s_add_i32 m0, s71, 0x1400
	s_nop 0
	global_load_lds_dwordx4 v228, s[62:63]
	v_add_u32_e32 v228, 0x80000, v228
	s_waitcnt lgkmcnt(3)
	v_mfma_f32_16x16x32_bf16 v[138:141], v[162:165], v[178:181], 0
	v_mfma_f32_16x16x32_bf16 v[154:157], v[162:165], v[194:197], 0
	ds_read_b128 v[162:165], v234 offset:12288
	s_waitcnt lgkmcnt(3)
	v_mfma_f32_16x16x32_bf16 v[138:141], v[166:169], v[182:185], v[138:141]
	v_mfma_f32_16x16x32_bf16 v[154:157], v[166:169], v[198:201], v[154:157]
	ds_read_b128 v[166:169], v235 offset:12288
	s_add_i32 m0, s71, 0x1800
	s_nop 0
	global_load_lds_dwordx4 v226, s[62:63]
	v_add_u32_e32 v226, 0x80000, v226
	s_waitcnt lgkmcnt(3)
	v_mfma_f32_16x16x32_bf16 v[138:141], v[170:173], v[186:189], v[138:141]
	v_mfma_f32_16x16x32_bf16 v[154:157], v[170:173], v[202:205], v[154:157]
	ds_read_b128 v[170:173], v236 offset:12288
	s_waitcnt lgkmcnt(3)
	v_mfma_f32_16x16x32_bf16 v[138:141], v[174:177], v[190:193], v[138:141]
	v_mfma_f32_16x16x32_bf16 v[154:157], v[174:177], v[206:209], v[154:157]
	ds_read_b128 v[174:177], v237 offset:12288
	s_add_i32 m0, s71, 0x1c00
	s_nop 0
	global_load_lds_dwordx4 v224, s[62:63]
	v_add_u32_e32 v224, 0x80000, v224
	s_waitcnt lgkmcnt(3)
	v_mfma_f32_16x16x32_bf16 v[142:145], v[162:165], v[178:181], 0
	v_mfma_f32_16x16x32_bf16 v[158:161], v[162:165], v[194:197], 0
	ds_read_b64_tr_b16 v[162:163], v242 offset:0
	ds_read_b64_tr_b16 v[164:165], v242 offset:8192
	s_waitcnt lgkmcnt(4)
	v_mfma_f32_16x16x32_bf16 v[142:145], v[166:169], v[182:185], v[142:145]
	v_mfma_f32_16x16x32_bf16 v[158:161], v[166:169], v[198:201], v[158:161]
	ds_read_b64_tr_b16 v[166:167], v242 offset:16384
	ds_read_b64_tr_b16 v[168:169], v242 offset:24576
	s_waitcnt lgkmcnt(5)
	v_mfma_f32_16x16x32_bf16 v[142:145], v[170:173], v[186:189], v[142:145]
	v_mfma_f32_16x16x32_bf16 v[158:161], v[170:173], v[202:205], v[158:161]
	ds_read_b64_tr_b16 v[170:171], v242 offset:256
	ds_read_b64_tr_b16 v[172:173], v242 offset:8448
	s_waitcnt lgkmcnt(6)
	v_mfma_f32_16x16x32_bf16 v[142:145], v[174:177], v[190:193], v[142:145]
	v_mfma_f32_16x16x32_bf16 v[158:161], v[174:177], v[206:209], v[158:161]
	ds_read_b64_tr_b16 v[174:175], v242 offset:16640
	ds_read_b64_tr_b16 v[176:177], v242 offset:24832
	s_add_i32 s4, s91, 0xb0
	s_cmp_le_u32 s4, s3
	s_cbranch_scc0 .Lat_diag_a
.Lat_sm_a:
	v_max3_f32 v238, v130, v131, v132
	v_max3_f32 v239, v146, v147, v148
	v_max3_f32 v238, v238, v133, v134
	v_max3_f32 v239, v239, v149, v150
	v_max3_f32 v238, v238, v135, v136
	v_max3_f32 v239, v239, v151, v152
	v_max3_f32 v238, v238, v137, v138
	v_max3_f32 v239, v239, v153, v154
	v_max3_f32 v238, v238, v139, v140
	v_max3_f32 v239, v239, v155, v156
	v_max3_f32 v238, v238, v141, v142
	v_max3_f32 v239, v239, v157, v158
	v_max3_f32 v238, v238, v143, v144
	v_max3_f32 v239, v239, v159, v160
	v_max_f32_e32 v238, v238, v145
	v_max_f32_e32 v239, v239, v161
	v_sub_f32_e32 v240, v238, v233
	v_sub_f32_e32 v241, v239, v243
	v_max_f32_e32 v240, v240, v241
	v_cmp_ge_f32_e32 vcc, s74, v240
	s_cmp_eq_u64 vcc, exec
	s_cbranch_scc0 .Lat_resc_a
.Lat_exp_a:
	v_sub_f32_e32 v130, v130, v233
	v_exp_f32_e32 v130, v130
	v_sub_f32_e32 v131, v131, v233
	v_exp_f32_e32 v131, v131
	v_sub_f32_e32 v132, v132, v233
	v_add_f32_e32 v0, v130, v131
	v_exp_f32_e32 v132, v132
	v_sub_f32_e32 v133, v133, v233
	v_add_f32_e32 v0, v0, v132
	v_exp_f32_e32 v133, v133
	v_sub_f32_e32 v134, v134, v233
	v_add_f32_e32 v0, v0, v133
	v_exp_f32_e32 v134, v134
	v_sub_f32_e32 v135, v135, v233
	v_add_f32_e32 v0, v0, v134
	v_exp_f32_e32 v135, v135
	v_sub_f32_e32 v136, v136, v233
	v_add_f32_e32 v0, v0, v135
	v_exp_f32_e32 v136, v136
	v_sub_f32_e32 v137, v137, v233
	v_add_f32_e32 v0, v0, v136
	v_exp_f32_e32 v137, v137
	v_sub_f32_e32 v138, v138, v233
	v_add_f32_e32 v0, v0, v137
	v_exp_f32_e32 v138, v138
	v_sub_f32_e32 v139, v139, v233
	v_add_f32_e32 v0, v0, v138
	v_exp_f32_e32 v139, v139
	v_sub_f32_e32 v140, v140, v233
	v_add_f32_e32 v0, v0, v139
	v_exp_f32_e32 v140, v140
	v_sub_f32_e32 v141, v141, v233
	v_add_f32_e32 v0, v0, v140
	v_exp_f32_e32 v141, v141
	v_sub_f32_e32 v142, v142, v233
	v_add_f32_e32 v0, v0, v141
	v_exp_f32_e32 v142, v142
	v_sub_f32_e32 v143, v143, v233
	v_add_f32_e32 v0, v0, v142
	v_exp_f32_e32 v143, v143
	v_sub_f32_e32 v144, v144, v233
	v_add_f32_e32 v0, v0, v143
	v_exp_f32_e32 v144, v144
	v_sub_f32_e32 v145, v145, v233
	v_add_f32_e32 v0, v0, v144
	v_exp_f32_e32 v145, v145
	v_cvt_pk_bf16_f32 v130, v130, v131
	v_cvt_pk_bf16_f32 v131, v132, v133
	v_cvt_pk_bf16_f32 v132, v134, v135
	v_cvt_pk_bf16_f32 v133, v136, v137
	v_cvt_pk_bf16_f32 v134, v138, v139
	v_cvt_pk_bf16_f32 v135, v140, v141
	v_cvt_pk_bf16_f32 v136, v142, v143
	v_add_f32_e32 v0, v0, v145
	v_cvt_pk_bf16_f32 v137, v144, v145
	v_add_f32_e32 v232, v232, v0
	v_sub_f32_e32 v146, v146, v243
	v_exp_f32_e32 v146, v146
	v_sub_f32_e32 v147, v147, v243
	v_exp_f32_e32 v147, v147
	v_sub_f32_e32 v148, v148, v243
	v_add_f32_e32 v0, v146, v147
	v_exp_f32_e32 v148, v148
	v_sub_f32_e32 v149, v149, v243
	v_add_f32_e32 v0, v0, v148
	v_exp_f32_e32 v149, v149
	v_sub_f32_e32 v150, v150, v243
	v_add_f32_e32 v0, v0, v149
	v_exp_f32_e32 v150, v150
	v_sub_f32_e32 v151, v151, v243
	v_add_f32_e32 v0, v0, v150
	v_exp_f32_e32 v151, v151
	v_sub_f32_e32 v152, v152, v243
	v_add_f32_e32 v0, v0, v151
	v_exp_f32_e32 v152, v152
	v_sub_f32_e32 v153, v153, v243
	v_add_f32_e32 v0, v0, v152
	v_exp_f32_e32 v153, v153
	v_sub_f32_e32 v154, v154, v243
	v_add_f32_e32 v0, v0, v153
	v_exp_f32_e32 v154, v154
	v_sub_f32_e32 v155, v155, v243
	v_add_f32_e32 v0, v0, v154
	v_exp_f32_e32 v155, v155
	v_sub_f32_e32 v156, v156, v243
	v_add_f32_e32 v0, v0, v155
	v_exp_f32_e32 v156, v156
	v_sub_f32_e32 v157, v157, v243
	v_add_f32_e32 v0, v0, v156
	v_exp_f32_e32 v157, v157
	v_sub_f32_e32 v158, v158, v243
	v_add_f32_e32 v0, v0, v157
	v_exp_f32_e32 v158, v158
	v_sub_f32_e32 v159, v159, v243
	v_add_f32_e32 v0, v0, v158
	v_exp_f32_e32 v159, v159
	v_sub_f32_e32 v160, v160, v243
	v_add_f32_e32 v0, v0, v159
	v_exp_f32_e32 v160, v160
	v_sub_f32_e32 v161, v161, v243
	v_add_f32_e32 v0, v0, v160
	v_exp_f32_e32 v161, v161
	v_cvt_pk_bf16_f32 v146, v146, v147
	v_cvt_pk_bf16_f32 v147, v148, v149
	v_cvt_pk_bf16_f32 v148, v150, v151
	v_cvt_pk_bf16_f32 v149, v152, v153
	v_cvt_pk_bf16_f32 v150, v154, v155
	v_cvt_pk_bf16_f32 v151, v156, v157
	v_cvt_pk_bf16_f32 v152, v158, v159
	v_add_f32_e32 v0, v0, v161
	v_cvt_pk_bf16_f32 v153, v160, v161
	v_add_f32_e32 v244, v244, v0
	s_waitcnt lgkmcnt(6)
	v_mfma_f32_16x16x32_bf16 v[114:117], v[162:165], v[130:133], v[114:117]
	v_mfma_f32_16x16x32_bf16 v[122:125], v[162:165], v[146:149], v[122:125]
	ds_read_b64_tr_b16 v[162:163], v242 offset:512
	ds_read_b64_tr_b16 v[164:165], v242 offset:8704
	s_waitcnt lgkmcnt(6)
	v_mfma_f32_16x16x32_bf16 v[114:117], v[166:169], v[134:137], v[114:117]
	v_mfma_f32_16x16x32_bf16 v[122:125], v[166:169], v[150:153], v[122:125]
	ds_read_b64_tr_b16 v[166:167], v242 offset:16896
	ds_read_b64_tr_b16 v[168:169], v242 offset:25088
	s_waitcnt lgkmcnt(6)
	v_mfma_f32_16x16x32_bf16 v[118:121], v[170:173], v[130:133], v[118:121]
	v_mfma_f32_16x16x32_bf16 v[126:129], v[170:173], v[146:149], v[126:129]
	ds_read_b64_tr_b16 v[170:171], v242 offset:768
	ds_read_b64_tr_b16 v[172:173], v242 offset:8960
	s_waitcnt lgkmcnt(6)
	v_mfma_f32_16x16x32_bf16 v[118:121], v[174:177], v[134:137], v[118:121]
	v_mfma_f32_16x16x32_bf16 v[126:129], v[174:177], v[150:153], v[126:129]
	ds_read_b64_tr_b16 v[174:175], v242 offset:17152
	ds_read_b64_tr_b16 v[176:177], v242 offset:25344
	s_waitcnt lgkmcnt(6)
	v_mfma_f32_16x16x32_bf16 v[98:101], v[162:165], v[130:133], v[98:101]
	v_mfma_f32_16x16x32_bf16 v[106:109], v[162:165], v[146:149], v[106:109]
	ds_read_b64_tr_b16 v[162:163], v242 offset:1024
	ds_read_b64_tr_b16 v[164:165], v242 offset:9216
	s_waitcnt lgkmcnt(6)
	v_mfma_f32_16x16x32_bf16 v[98:101], v[166:169], v[134:137], v[98:101]
	v_mfma_f32_16x16x32_bf16 v[106:109], v[166:169], v[150:153], v[106:109]
	ds_read_b64_tr_b16 v[166:167], v242 offset:17408
	ds_read_b64_tr_b16 v[168:169], v242 offset:25600
	s_waitcnt lgkmcnt(6)
	v_mfma_f32_16x16x32_bf16 v[102:105], v[170:173], v[130:133], v[102:105]
	v_mfma_f32_16x16x32_bf16 v[110:113], v[170:173], v[146:149], v[110:113]
	ds_read_b64_tr_b16 v[170:171], v242 offset:1280
	ds_read_b64_tr_b16 v[172:173], v242 offset:9472
	s_waitcnt lgkmcnt(6)
	v_mfma_f32_16x16x32_bf16 v[102:105], v[174:177], v[134:137], v[102:105]
	v_mfma_f32_16x16x32_bf16 v[110:113], v[174:177], v[150:153], v[110:113]
	ds_read_b64_tr_b16 v[174:175], v242 offset:17664
	ds_read_b64_tr_b16 v[176:177], v242 offset:25856
	s_waitcnt lgkmcnt(6)
	v_mfma_f32_16x16x32_bf16 v[82:85], v[162:165], v[130:133], v[82:85]
	v_mfma_f32_16x16x32_bf16 v[90:93], v[162:165], v[146:149], v[90:93]
	ds_read_b64_tr_b16 v[162:163], v242 offset:1536
	ds_read_b64_tr_b16 v[164:165], v242 offset:9728
	s_waitcnt lgkmcnt(6)
	v_mfma_f32_16x16x32_bf16 v[82:85], v[166:169], v[134:137], v[82:85]
	v_mfma_f32_16x16x32_bf16 v[90:93], v[166:169], v[150:153], v[90:93]
	ds_read_b64_tr_b16 v[166:167], v242 offset:17920
	ds_read_b64_tr_b16 v[168:169], v242 offset:26112
	s_waitcnt lgkmcnt(6)
	v_mfma_f32_16x16x32_bf16 v[86:89], v[170:173], v[130:133], v[86:89]
	v_mfma_f32_16x16x32_bf16 v[94:97], v[170:173], v[146:149], v[94:97]
	ds_read_b64_tr_b16 v[170:171], v242 offset:1792
	ds_read_b64_tr_b16 v[172:173], v242 offset:9984
	s_waitcnt lgkmcnt(6)
	v_mfma_f32_16x16x32_bf16 v[86:89], v[174:177], v[134:137], v[86:89]
	v_mfma_f32_16x16x32_bf16 v[94:97], v[174:177], v[150:153], v[94:97]
	ds_read_b64_tr_b16 v[174:175], v242 offset:18176
	ds_read_b64_tr_b16 v[176:177], v242 offset:26368
	s_waitcnt lgkmcnt(6)
	v_mfma_f32_16x16x32_bf16 v[66:69], v[162:165], v[130:133], v[66:69]
	v_mfma_f32_16x16x32_bf16 v[74:77], v[162:165], v[146:149], v[74:77]
	ds_read_b64_tr_b16 v[162:163], v242 offset:2048
	ds_read_b64_tr_b16 v[164:165], v242 offset:10240
	s_waitcnt lgkmcnt(6)
	v_mfma_f32_16x16x32_bf16 v[66:69], v[166:169], v[134:137], v[66:69]
	v_mfma_f32_16x16x32_bf16 v[74:77], v[166:169], v[150:153], v[74:77]
	ds_read_b64_tr_b16 v[166:167], v242 offset:18432
	ds_read_b64_tr_b16 v[168:169], v242 offset:26624
	s_waitcnt lgkmcnt(6)
	v_mfma_f32_16x16x32_bf16 v[70:73], v[170:173], v[130:133], v[70:73]
	v_mfma_f32_16x16x32_bf16 v[78:81], v[170:173], v[146:149], v[78:81]
	ds_read_b64_tr_b16 v[170:171], v242 offset:2304
	ds_read_b64_tr_b16 v[172:173], v242 offset:10496
	s_waitcnt lgkmcnt(6)
	v_mfma_f32_16x16x32_bf16 v[70:73], v[174:177], v[134:137], v[70:73]
	v_mfma_f32_16x16x32_bf16 v[78:81], v[174:177], v[150:153], v[78:81]
	ds_read_b64_tr_b16 v[174:175], v242 offset:18688
	ds_read_b64_tr_b16 v[176:177], v242 offset:26880
	s_waitcnt lgkmcnt(6)
	v_mfma_f32_16x16x32_bf16 v[50:53], v[162:165], v[130:133], v[50:53]
	v_mfma_f32_16x16x32_bf16 v[58:61], v[162:165], v[146:149], v[58:61]
	ds_read_b64_tr_b16 v[162:163], v242 offset:2560
	ds_read_b64_tr_b16 v[164:165], v242 offset:10752
	s_waitcnt lgkmcnt(6)
	v_mfma_f32_16x16x32_bf16 v[50:53], v[166:169], v[134:137], v[50:53]
	v_mfma_f32_16x16x32_bf16 v[58:61], v[166:169], v[150:153], v[58:61]
	ds_read_b64_tr_b16 v[166:167], v242 offset:18944
	ds_read_b64_tr_b16 v[168:169], v242 offset:27136
	s_waitcnt lgkmcnt(6)
	v_mfma_f32_16x16x32_bf16 v[54:57], v[170:173], v[130:133], v[54:57]
	v_mfma_f32_16x16x32_bf16 v[62:65], v[170:173], v[146:149], v[62:65]
	ds_read_b64_tr_b16 v[170:171], v242 offset:2816
	ds_read_b64_tr_b16 v[172:173], v242 offset:11008
	s_waitcnt lgkmcnt(6)
	v_mfma_f32_16x16x32_bf16 v[54:57], v[174:177], v[134:137], v[54:57]
	v_mfma_f32_16x16x32_bf16 v[62:65], v[174:177], v[150:153], v[62:65]
	ds_read_b64_tr_b16 v[174:175], v242 offset:19200
	ds_read_b64_tr_b16 v[176:177], v242 offset:27392
	s_waitcnt lgkmcnt(6)
	v_mfma_f32_16x16x32_bf16 v[34:37], v[162:165], v[130:133], v[34:37]
	v_mfma_f32_16x16x32_bf16 v[42:45], v[162:165], v[146:149], v[42:45]
	ds_read_b64_tr_b16 v[162:163], v242 offset:3072
	ds_read_b64_tr_b16 v[164:165], v242 offset:11264
	s_waitcnt lgkmcnt(6)
	v_mfma_f32_16x16x32_bf16 v[34:37], v[166:169], v[134:137], v[34:37]
	v_mfma_f32_16x16x32_bf16 v[42:45], v[166:169], v[150:153], v[42:45]
	ds_read_b64_tr_b16 v[166:167], v242 offset:19456
	ds_read_b64_tr_b16 v[168:169], v242 offset:27648
	s_waitcnt lgkmcnt(6)
	v_mfma_f32_16x16x32_bf16 v[38:41], v[170:173], v[130:133], v[38:41]
	v_mfma_f32_16x16x32_bf16 v[46:49], v[170:173], v[146:149], v[46:49]
	ds_read_b64_tr_b16 v[170:171], v242 offset:3328
	ds_read_b64_tr_b16 v[172:173], v242 offset:11520
	s_waitcnt lgkmcnt(6)
	v_mfma_f32_16x16x32_bf16 v[38:41], v[174:177], v[134:137], v[38:41]
	v_mfma_f32_16x16x32_bf16 v[46:49], v[174:177], v[150:153], v[46:49]
	ds_read_b64_tr_b16 v[174:175], v242 offset:19712
	ds_read_b64_tr_b16 v[176:177], v242 offset:27904
	s_waitcnt lgkmcnt(6)
	v_mfma_f32_16x16x32_bf16 v[18:21], v[162:165], v[130:133], v[18:21]
	v_mfma_f32_16x16x32_bf16 v[26:29], v[162:165], v[146:149], v[26:29]
	ds_read_b64_tr_b16 v[162:163], v242 offset:3584
	ds_read_b64_tr_b16 v[164:165], v242 offset:11776
	s_waitcnt lgkmcnt(6)
	v_mfma_f32_16x16x32_bf16 v[18:21], v[166:169], v[134:137], v[18:21]
	v_mfma_f32_16x16x32_bf16 v[26:29], v[166:169], v[150:153], v[26:29]
	ds_read_b64_tr_b16 v[166:167], v242 offset:19968
	ds_read_b64_tr_b16 v[168:169], v242 offset:28160
	s_waitcnt lgkmcnt(6)
	v_mfma_f32_16x16x32_bf16 v[22:25], v[170:173], v[130:133], v[22:25]
	v_mfma_f32_16x16x32_bf16 v[30:33], v[170:173], v[146:149], v[30:33]
	ds_read_b64_tr_b16 v[170:171], v242 offset:3840
	ds_read_b64_tr_b16 v[172:173], v242 offset:12032
	s_waitcnt lgkmcnt(6)
	v_mfma_f32_16x16x32_bf16 v[22:25], v[174:177], v[134:137], v[22:25]
	v_mfma_f32_16x16x32_bf16 v[30:33], v[174:177], v[150:153], v[30:33]
	ds_read_b64_tr_b16 v[174:175], v242 offset:20224
	ds_read_b64_tr_b16 v[176:177], v242 offset:28416
	s_waitcnt lgkmcnt(6)
	v_mfma_f32_16x16x32_bf16 v[2:5], v[162:165], v[130:133], v[2:5]
	v_mfma_f32_16x16x32_bf16 v[10:13], v[162:165], v[146:149], v[10:13]
	s_waitcnt lgkmcnt(4)
	v_mfma_f32_16x16x32_bf16 v[2:5], v[166:169], v[134:137], v[2:5]
	v_mfma_f32_16x16x32_bf16 v[10:13], v[166:169], v[150:153], v[10:13]
	s_waitcnt lgkmcnt(2)
	v_mfma_f32_16x16x32_bf16 v[6:9], v[170:173], v[130:133], v[6:9]
	v_mfma_f32_16x16x32_bf16 v[14:17], v[170:173], v[146:149], v[14:17]
	s_waitcnt lgkmcnt(0)
	v_mfma_f32_16x16x32_bf16 v[6:9], v[174:177], v[134:137], v[6:9]
	v_mfma_f32_16x16x32_bf16 v[14:17], v[174:177], v[150:153], v[14:17]
	s_xor_b32 s4, s70, 0x10000
	v_xor_b32_e32 v234, s4, v221
	v_xor_b32_e32 v235, 64, v234
	v_xor_b32_e32 v236, 0x80, v234
	v_xor_b32_e32 v237, 0xc0, v234
	s_branch .Lat_end_a
.Lat_resc_a:
	s_nop 1
	v_permlane16_swap_b32_e32 v238, v239
	v_max_f32_e32 v238, v238, v239
	v_mov_b32_e32 v239, v238
	s_nop 1
	v_permlane32_swap_b32_e32 v238, v239
	v_max_f32_e32 v238, v238, v239
	v_mov_b32_e32 v239, v238
	s_nop 1
	v_permlane16_swap_b32_e32 v238, v239
	v_max_f32_e32 v240, v233, v238
	v_sub_f32_e32 v241, v233, v240
	v_exp_f32_e32 v241, v241
	v_mov_b32_e32 v233, v240
	v_mul_f32_e32 v232, v232, v241
	v_mul_f32_e32 v114, v114, v241
	v_mul_f32_e32 v115, v115, v241
	v_mul_f32_e32 v116, v116, v241
	v_mul_f32_e32 v117, v117, v241
	v_mul_f32_e32 v118, v118, v241
	v_mul_f32_e32 v119, v119, v241
	v_mul_f32_e32 v120, v120, v241
	v_mul_f32_e32 v121, v121, v241
	v_mul_f32_e32 v98, v98, v241
	v_mul_f32_e32 v99, v99, v241
	v_mul_f32_e32 v100, v100, v241
	v_mul_f32_e32 v101, v101, v241
	v_mul_f32_e32 v102, v102, v241
	v_mul_f32_e32 v103, v103, v241
	v_mul_f32_e32 v104, v104, v241
	v_mul_f32_e32 v105, v105, v241
	v_mul_f32_e32 v82, v82, v241
	v_mul_f32_e32 v83, v83, v241
	v_mul_f32_e32 v84, v84, v241
	v_mul_f32_e32 v85, v85, v241
	v_mul_f32_e32 v86, v86, v241
	v_mul_f32_e32 v87, v87, v241
	v_mul_f32_e32 v88, v88, v241
	v_mul_f32_e32 v89, v89, v241
	v_mul_f32_e32 v66, v66, v241
	v_mul_f32_e32 v67, v67, v241
	v_mul_f32_e32 v68, v68, v241
	v_mul_f32_e32 v69, v69, v241
	v_mul_f32_e32 v70, v70, v241
	v_mul_f32_e32 v71, v71, v241
	v_mul_f32_e32 v72, v72, v241
	v_mul_f32_e32 v73, v73, v241
	v_mul_f32_e32 v50, v50, v241
	v_mul_f32_e32 v51, v51, v241
	v_mul_f32_e32 v52, v52, v241
	v_mul_f32_e32 v53, v53, v241
	v_mul_f32_e32 v54, v54, v241
	v_mul_f32_e32 v55, v55, v241
	v_mul_f32_e32 v56, v56, v241
	v_mul_f32_e32 v57, v57, v241
	v_mul_f32_e32 v34, v34, v241
	v_mul_f32_e32 v35, v35, v241
	v_mul_f32_e32 v36, v36, v241
	v_mul_f32_e32 v37, v37, v241
	v_mul_f32_e32 v38, v38, v241
	v_mul_f32_e32 v39, v39, v241
	v_mul_f32_e32 v40, v40, v241
	v_mul_f32_e32 v41, v41, v241
	v_mul_f32_e32 v18, v18, v241
	v_mul_f32_e32 v19, v19, v241
	v_mul_f32_e32 v20, v20, v241
	v_mul_f32_e32 v21, v21, v241
	v_mul_f32_e32 v22, v22, v241
	v_mul_f32_e32 v23, v23, v241
	v_mul_f32_e32 v24, v24, v241
	v_mul_f32_e32 v25, v25, v241
	v_mul_f32_e32 v2, v2, v241
	v_mul_f32_e32 v3, v3, v241
	v_mul_f32_e32 v4, v4, v241
	v_mul_f32_e32 v5, v5, v241
	v_mul_f32_e32 v6, v6, v241
	v_mul_f32_e32 v7, v7, v241
	v_mul_f32_e32 v8, v8, v241
	v_mul_f32_e32 v9, v9, v241
	v_max_f32_e32 v240, v243, v239
	v_sub_f32_e32 v241, v243, v240
	v_exp_f32_e32 v241, v241
	v_mov_b32_e32 v243, v240
	v_mul_f32_e32 v244, v244, v241
	v_mul_f32_e32 v122, v122, v241
	v_mul_f32_e32 v123, v123, v241
	v_mul_f32_e32 v124, v124, v241
	v_mul_f32_e32 v125, v125, v241
	v_mul_f32_e32 v126, v126, v241
	v_mul_f32_e32 v127, v127, v241
	v_mul_f32_e32 v128, v128, v241
	v_mul_f32_e32 v129, v129, v241
	v_mul_f32_e32 v106, v106, v241
	v_mul_f32_e32 v107, v107, v241
	v_mul_f32_e32 v108, v108, v241
	v_mul_f32_e32 v109, v109, v241
	v_mul_f32_e32 v110, v110, v241
	v_mul_f32_e32 v111, v111, v241
	v_mul_f32_e32 v112, v112, v241
	v_mul_f32_e32 v113, v113, v241
	v_mul_f32_e32 v90, v90, v241
	v_mul_f32_e32 v91, v91, v241
	v_mul_f32_e32 v92, v92, v241
	v_mul_f32_e32 v93, v93, v241
	v_mul_f32_e32 v94, v94, v241
	v_mul_f32_e32 v95, v95, v241
	v_mul_f32_e32 v96, v96, v241
	v_mul_f32_e32 v97, v97, v241
	v_mul_f32_e32 v74, v74, v241
	v_mul_f32_e32 v75, v75, v241
	v_mul_f32_e32 v76, v76, v241
	v_mul_f32_e32 v77, v77, v241
	v_mul_f32_e32 v78, v78, v241
	v_mul_f32_e32 v79, v79, v241
	v_mul_f32_e32 v80, v80, v241
	v_mul_f32_e32 v81, v81, v241
	v_mul_f32_e32 v58, v58, v241
	v_mul_f32_e32 v59, v59, v241
	v_mul_f32_e32 v60, v60, v241
	v_mul_f32_e32 v61, v61, v241
	v_mul_f32_e32 v62, v62, v241
	v_mul_f32_e32 v63, v63, v241
	v_mul_f32_e32 v64, v64, v241
	v_mul_f32_e32 v65, v65, v241
	v_mul_f32_e32 v42, v42, v241
	v_mul_f32_e32 v43, v43, v241
	v_mul_f32_e32 v44, v44, v241
	v_mul_f32_e32 v45, v45, v241
	v_mul_f32_e32 v46, v46, v241
	v_mul_f32_e32 v47, v47, v241
	v_mul_f32_e32 v48, v48, v241
	v_mul_f32_e32 v49, v49, v241
	v_mul_f32_e32 v26, v26, v241
	v_mul_f32_e32 v27, v27, v241
	v_mul_f32_e32 v28, v28, v241
	v_mul_f32_e32 v29, v29, v241
	v_mul_f32_e32 v30, v30, v241
	v_mul_f32_e32 v31, v31, v241
	v_mul_f32_e32 v32, v32, v241
	v_mul_f32_e32 v33, v33, v241
	v_mul_f32_e32 v10, v10, v241
	v_mul_f32_e32 v11, v11, v241
	v_mul_f32_e32 v12, v12, v241
	v_mul_f32_e32 v13, v13, v241
	v_mul_f32_e32 v14, v14, v241
	v_mul_f32_e32 v15, v15, v241
	v_mul_f32_e32 v16, v16, v241
	v_mul_f32_e32 v17, v17, v241
	s_branch .Lat_exp_a
.Lat_diag_a:
	s_nop 7
	v_subrev_u32_e32 v234, 0, v223
	v_cmp_gt_i32_e64 s[4:5], 0, v234
	v_med3_i32 v234, v234, 0, s81
	v_lshl_add_u32 v234, v234, 2, s50
	ds_read_b32 v238, v234
	v_subrev_u32_e32 v235, 1, v223
	v_cmp_gt_i32_e64 s[6:7], 0, v235
	v_med3_i32 v235, v235, 0, s81
	v_lshl_add_u32 v235, v235, 2, s50
	ds_read_b32 v239, v235
	v_subrev_u32_e32 v236, 2, v223
	v_cmp_gt_i32_e64 s[8:9], 0, v236
	v_med3_i32 v236, v236, 0, s81
	v_lshl_add_u32 v236, v236, 2, s50
	ds_read_b32 v240, v236
	v_subrev_u32_e32 v237, 3, v223
	v_cmp_gt_i32_e64 s[10:11], 0, v237
	v_med3_i32 v237, v237, 0, s81
	v_lshl_add_u32 v237, v237, 2, s50
	ds_read_b32 v241, v237
	s_waitcnt lgkmcnt(0)
	v_add_f32_e32 v130, v130, v238
	v_cndmask_b32_e64 v130, v130, v216, s[4:5]
	v_add_f32_e32 v131, v131, v239
	v_cndmask_b32_e64 v131, v131, v216, s[6:7]
	v_add_f32_e32 v132, v132, v240
	v_cndmask_b32_e64 v132, v132, v216, s[8:9]
	v_add_f32_e32 v133, v133, v241
	v_cndmask_b32_e64 v133, v133, v216, s[10:11]
	v_subrev_u32_e32 v234, 16, v223
	v_cmp_gt_i32_e64 s[4:5], 0, v234
	v_med3_i32 v234, v234, 0, s81
	v_lshl_add_u32 v234, v234, 2, s50
	ds_read_b32 v238, v234
	v_subrev_u32_e32 v235, 17, v223
	v_cmp_gt_i32_e64 s[6:7], 0, v235
	v_med3_i32 v235, v235, 0, s81
	v_lshl_add_u32 v235, v235, 2, s50
	ds_read_b32 v239, v235
	v_subrev_u32_e32 v236, 18, v223
	v_cmp_gt_i32_e64 s[8:9], 0, v236
	v_med3_i32 v236, v236, 0, s81
	v_lshl_add_u32 v236, v236, 2, s50
	ds_read_b32 v240, v236
	v_subrev_u32_e32 v237, 19, v223
	v_cmp_gt_i32_e64 s[10:11], 0, v237
	v_med3_i32 v237, v237, 0, s81
	v_lshl_add_u32 v237, v237, 2, s50
	ds_read_b32 v241, v237
	s_waitcnt lgkmcnt(0)
	v_add_f32_e32 v134, v134, v238
	v_cndmask_b32_e64 v134, v134, v216, s[4:5]
	v_add_f32_e32 v135, v135, v239
	v_cndmask_b32_e64 v135, v135, v216, s[6:7]
	v_add_f32_e32 v136, v136, v240
	v_cndmask_b32_e64 v136, v136, v216, s[8:9]
	v_add_f32_e32 v137, v137, v241
	v_cndmask_b32_e64 v137, v137, v216, s[10:11]
	v_subrev_u32_e32 v234, 32, v223
	v_cmp_gt_i32_e64 s[4:5], 0, v234
	v_med3_i32 v234, v234, 0, s81
	v_lshl_add_u32 v234, v234, 2, s50
	ds_read_b32 v238, v234
	v_subrev_u32_e32 v235, 33, v223
	v_cmp_gt_i32_e64 s[6:7], 0, v235
	v_med3_i32 v235, v235, 0, s81
	v_lshl_add_u32 v235, v235, 2, s50
	ds_read_b32 v239, v235
	v_subrev_u32_e32 v236, 34, v223
	v_cmp_gt_i32_e64 s[8:9], 0, v236
	v_med3_i32 v236, v236, 0, s81
	v_lshl_add_u32 v236, v236, 2, s50
	ds_read_b32 v240, v236
	v_subrev_u32_e32 v237, 35, v223
	v_cmp_gt_i32_e64 s[10:11], 0, v237
	v_med3_i32 v237, v237, 0, s81
	v_lshl_add_u32 v237, v237, 2, s50
	ds_read_b32 v241, v237
	s_waitcnt lgkmcnt(0)
	v_add_f32_e32 v138, v138, v238
	v_cndmask_b32_e64 v138, v138, v216, s[4:5]
	v_add_f32_e32 v139, v139, v239
	v_cndmask_b32_e64 v139, v139, v216, s[6:7]
	v_add_f32_e32 v140, v140, v240
	v_cndmask_b32_e64 v140, v140, v216, s[8:9]
	v_add_f32_e32 v141, v141, v241
	v_cndmask_b32_e64 v141, v141, v216, s[10:11]
	v_subrev_u32_e32 v234, 48, v223
	v_cmp_gt_i32_e64 s[4:5], 0, v234
	v_med3_i32 v234, v234, 0, s81
	v_lshl_add_u32 v234, v234, 2, s50
	ds_read_b32 v238, v234
	v_subrev_u32_e32 v235, 49, v223
	v_cmp_gt_i32_e64 s[6:7], 0, v235
	v_med3_i32 v235, v235, 0, s81
	v_lshl_add_u32 v235, v235, 2, s50
	ds_read_b32 v239, v235
	v_subrev_u32_e32 v236, 50, v223
	v_cmp_gt_i32_e64 s[8:9], 0, v236
	v_med3_i32 v236, v236, 0, s81
	v_lshl_add_u32 v236, v236, 2, s50
	ds_read_b32 v240, v236
	v_subrev_u32_e32 v237, 51, v223
	v_cmp_gt_i32_e64 s[10:11], 0, v237
	v_med3_i32 v237, v237, 0, s81
	v_lshl_add_u32 v237, v237, 2, s50
	ds_read_b32 v241, v237
	s_waitcnt lgkmcnt(0)
	v_add_f32_e32 v142, v142, v238
	v_cndmask_b32_e64 v142, v142, v216, s[4:5]
	v_add_f32_e32 v143, v143, v239
	v_cndmask_b32_e64 v143, v143, v216, s[6:7]
	v_add_f32_e32 v144, v144, v240
	v_cndmask_b32_e64 v144, v144, v216, s[8:9]
	v_add_f32_e32 v145, v145, v241
	v_cndmask_b32_e64 v145, v145, v216, s[10:11]
	v_subrev_u32_e32 v234, -16, v223
	v_cmp_gt_i32_e64 s[4:5], 0, v234
	v_med3_i32 v234, v234, 0, s81
	v_lshl_add_u32 v234, v234, 2, s50
	ds_read_b32 v238, v234
	v_subrev_u32_e32 v235, -15, v223
	v_cmp_gt_i32_e64 s[6:7], 0, v235
	v_med3_i32 v235, v235, 0, s81
	v_lshl_add_u32 v235, v235, 2, s50
	ds_read_b32 v239, v235
	v_subrev_u32_e32 v236, -14, v223
	v_cmp_gt_i32_e64 s[8:9], 0, v236
	v_med3_i32 v236, v236, 0, s81
	v_lshl_add_u32 v236, v236, 2, s50
	ds_read_b32 v240, v236
	v_subrev_u32_e32 v237, -13, v223
	v_cmp_gt_i32_e64 s[10:11], 0, v237
	v_med3_i32 v237, v237, 0, s81
	v_lshl_add_u32 v237, v237, 2, s50
	ds_read_b32 v241, v237
	s_waitcnt lgkmcnt(0)
	v_add_f32_e32 v146, v146, v238
	v_cndmask_b32_e64 v146, v146, v216, s[4:5]
	v_add_f32_e32 v147, v147, v239
	v_cndmask_b32_e64 v147, v147, v216, s[6:7]
	v_add_f32_e32 v148, v148, v240
	v_cndmask_b32_e64 v148, v148, v216, s[8:9]
	v_add_f32_e32 v149, v149, v241
	v_cndmask_b32_e64 v149, v149, v216, s[10:11]
	v_subrev_u32_e32 v234, 0, v223
	v_cmp_gt_i32_e64 s[4:5], 0, v234
	v_med3_i32 v234, v234, 0, s81
	v_lshl_add_u32 v234, v234, 2, s50
	ds_read_b32 v238, v234
	v_subrev_u32_e32 v235, 1, v223
	v_cmp_gt_i32_e64 s[6:7], 0, v235
	v_med3_i32 v235, v235, 0, s81
	v_lshl_add_u32 v235, v235, 2, s50
	ds_read_b32 v239, v235
	v_subrev_u32_e32 v236, 2, v223
	v_cmp_gt_i32_e64 s[8:9], 0, v236
	v_med3_i32 v236, v236, 0, s81
	v_lshl_add_u32 v236, v236, 2, s50
	ds_read_b32 v240, v236
	v_subrev_u32_e32 v237, 3, v223
	v_cmp_gt_i32_e64 s[10:11], 0, v237
	v_med3_i32 v237, v237, 0, s81
	v_lshl_add_u32 v237, v237, 2, s50
	ds_read_b32 v241, v237
	s_waitcnt lgkmcnt(0)
	v_add_f32_e32 v150, v150, v238
	v_cndmask_b32_e64 v150, v150, v216, s[4:5]
	v_add_f32_e32 v151, v151, v239
	v_cndmask_b32_e64 v151, v151, v216, s[6:7]
	v_add_f32_e32 v152, v152, v240
	v_cndmask_b32_e64 v152, v152, v216, s[8:9]
	v_add_f32_e32 v153, v153, v241
	v_cndmask_b32_e64 v153, v153, v216, s[10:11]
	v_subrev_u32_e32 v234, 16, v223
	v_cmp_gt_i32_e64 s[4:5], 0, v234
	v_med3_i32 v234, v234, 0, s81
	v_lshl_add_u32 v234, v234, 2, s50
	ds_read_b32 v238, v234
	v_subrev_u32_e32 v235, 17, v223
	v_cmp_gt_i32_e64 s[6:7], 0, v235
	v_med3_i32 v235, v235, 0, s81
	v_lshl_add_u32 v235, v235, 2, s50
	ds_read_b32 v239, v235
	v_subrev_u32_e32 v236, 18, v223
	v_cmp_gt_i32_e64 s[8:9], 0, v236
	v_med3_i32 v236, v236, 0, s81
	v_lshl_add_u32 v236, v236, 2, s50
	ds_read_b32 v240, v236
	v_subrev_u32_e32 v237, 19, v223
	v_cmp_gt_i32_e64 s[10:11], 0, v237
	v_med3_i32 v237, v237, 0, s81
	v_lshl_add_u32 v237, v237, 2, s50
	ds_read_b32 v241, v237
	s_waitcnt lgkmcnt(0)
	v_add_f32_e32 v154, v154, v238
	v_cndmask_b32_e64 v154, v154, v216, s[4:5]
	v_add_f32_e32 v155, v155, v239
	v_cndmask_b32_e64 v155, v155, v216, s[6:7]
	v_add_f32_e32 v156, v156, v240
	v_cndmask_b32_e64 v156, v156, v216, s[8:9]
	v_add_f32_e32 v157, v157, v241
	v_cndmask_b32_e64 v157, v157, v216, s[10:11]
	v_subrev_u32_e32 v234, 32, v223
	v_cmp_gt_i32_e64 s[4:5], 0, v234
	v_med3_i32 v234, v234, 0, s81
	v_lshl_add_u32 v234, v234, 2, s50
	ds_read_b32 v238, v234
	v_subrev_u32_e32 v235, 33, v223
	v_cmp_gt_i32_e64 s[6:7], 0, v235
	v_med3_i32 v235, v235, 0, s81
	v_lshl_add_u32 v235, v235, 2, s50
	ds_read_b32 v239, v235
	v_subrev_u32_e32 v236, 34, v223
	v_cmp_gt_i32_e64 s[8:9], 0, v236
	v_med3_i32 v236, v236, 0, s81
	v_lshl_add_u32 v236, v236, 2, s50
	ds_read_b32 v240, v236
	v_subrev_u32_e32 v237, 35, v223
	v_cmp_gt_i32_e64 s[10:11], 0, v237
	v_med3_i32 v237, v237, 0, s81
	v_lshl_add_u32 v237, v237, 2, s50
	ds_read_b32 v241, v237
	s_waitcnt lgkmcnt(0)
	v_add_f32_e32 v158, v158, v238
	v_cndmask_b32_e64 v158, v158, v216, s[4:5]
	v_add_f32_e32 v159, v159, v239
	v_cndmask_b32_e64 v159, v159, v216, s[6:7]
	v_add_f32_e32 v160, v160, v240
	v_cndmask_b32_e64 v160, v160, v216, s[8:9]
	v_add_f32_e32 v161, v161, v241
	v_cndmask_b32_e64 v161, v161, v216, s[10:11]
	s_branch .Lat_sm_a
.Lat_end_a:
.Lat_next:
	s_add_i32 s58, s58, 1
	s_xor_b32 s70, s70, 0x10000
	s_xor_b32 s71, s71, 0x10000
	v_add_u32_e32 v223, 0xffffffc0, v223
	s_addk_i32 s91, 0x40
	s_cmp_le_u32 s58, s88
	s_cbranch_scc1 .Lat_loop
	s_waitcnt vmcnt(0) lgkmcnt(0)
	s_barrier
	s_cmp_gt_u32 s58, s89
	s_cbranch_scc1 .Lat_done
	ds_read_b128 v[162:165], v234
	ds_read_b128 v[166:169], v235
	ds_read_b128 v[170:173], v236
	ds_read_b128 v[174:177], v237
	v_add_u32_e32 v242, s70, v222
	s_waitcnt lgkmcnt(3)
	v_mfma_f32_16x16x32_bf16 v[130:133], v[162:165], v[178:181], 0
	v_mfma_f32_16x16x32_bf16 v[146:149], v[162:165], v[194:197], 0
	ds_read_b128 v[162:165], v234 offset:4096
	s_waitcnt lgkmcnt(3)
	v_mfma_f32_16x16x32_bf16 v[130:133], v[166:169], v[182:185], v[130:133]
	v_mfma_f32_16x16x32_bf16 v[146:149], v[166:169], v[198:201], v[146:149]
	ds_read_b128 v[166:169], v235 offset:4096
	s_waitcnt lgkmcnt(3)
	v_mfma_f32_16x16x32_bf16 v[130:133], v[170:173], v[186:189], v[130:133]
	v_mfma_f32_16x16x32_bf16 v[146:149], v[170:173], v[202:205], v[146:149]
	ds_read_b128 v[170:173], v236 offset:4096
	s_waitcnt lgkmcnt(3)
	v_mfma_f32_16x16x32_bf16 v[130:133], v[174:177], v[190:193], v[130:133]
	v_mfma_f32_16x16x32_bf16 v[146:149], v[174:177], v[206:209], v[146:149]
	ds_read_b128 v[174:177], v237 offset:4096
	s_waitcnt lgkmcnt(3)
	v_mfma_f32_16x16x32_bf16 v[134:137], v[162:165], v[178:181], 0
	v_mfma_f32_16x16x32_bf16 v[150:153], v[162:165], v[194:197], 0
	ds_read_b128 v[162:165], v234 offset:8192
	s_waitcnt lgkmcnt(3)
	v_mfma_f32_16x16x32_bf16 v[134:137], v[166:169], v[182:185], v[134:137]
	v_mfma_f32_16x16x32_bf16 v[150:153], v[166:169], v[198:201], v[150:153]
	ds_read_b128 v[166:169], v235 offset:8192
	s_waitcnt lgkmcnt(3)
	v_mfma_f32_16x16x32_bf16 v[134:137], v[170:173], v[186:189], v[134:137]
	v_mfma_f32_16x16x32_bf16 v[150:153], v[170:173], v[202:205], v[150:153]
	ds_read_b128 v[170:173], v236 offset:8192
	s_waitcnt lgkmcnt(3)
	v_mfma_f32_16x16x32_bf16 v[134:137], v[174:177], v[190:193], v[134:137]
	v_mfma_f32_16x16x32_bf16 v[150:153], v[174:177], v[206:209], v[150:153]
	ds_read_b128 v[174:177], v237 offset:8192
	s_waitcnt lgkmcnt(3)
	v_mfma_f32_16x16x32_bf16 v[138:141], v[162:165], v[178:181], 0
	v_mfma_f32_16x16x32_bf16 v[154:157], v[162:165], v[194:197], 0
	ds_read_b128 v[162:165], v234 offset:12288
	s_waitcnt lgkmcnt(3)
	v_mfma_f32_16x16x32_bf16 v[138:141], v[166:169], v[182:185], v[138:141]
	v_mfma_f32_16x16x32_bf16 v[154:157], v[166:169], v[198:201], v[154:157]
	ds_read_b128 v[166:169], v235 offset:12288
	s_waitcnt lgkmcnt(3)
	v_mfma_f32_16x16x32_bf16 v[138:141], v[170:173], v[186:189], v[138:141]
	v_mfma_f32_16x16x32_bf16 v[154:157], v[170:173], v[202:205], v[154:157]
	ds_read_b128 v[170:173], v236 offset:12288
	s_waitcnt lgkmcnt(3)
	v_mfma_f32_16x16x32_bf16 v[138:141], v[174:177], v[190:193], v[138:141]
	v_mfma_f32_16x16x32_bf16 v[154:157], v[174:177], v[206:209], v[154:157]
	ds_read_b128 v[174:177], v237 offset:12288
	s_waitcnt lgkmcnt(3)
	v_mfma_f32_16x16x32_bf16 v[142:145], v[162:165], v[178:181], 0
	v_mfma_f32_16x16x32_bf16 v[158:161], v[162:165], v[194:197], 0
	ds_read_b64_tr_b16 v[162:163], v242 offset:0
	ds_read_b64_tr_b16 v[164:165], v242 offset:8192
	s_waitcnt lgkmcnt(4)
	v_mfma_f32_16x16x32_bf16 v[142:145], v[166:169], v[182:185], v[142:145]
	v_mfma_f32_16x16x32_bf16 v[158:161], v[166:169], v[198:201], v[158:161]
	ds_read_b64_tr_b16 v[166:167], v242 offset:16384
	ds_read_b64_tr_b16 v[168:169], v242 offset:24576
	s_waitcnt lgkmcnt(5)
	v_mfma_f32_16x16x32_bf16 v[142:145], v[170:173], v[186:189], v[142:145]
	v_mfma_f32_16x16x32_bf16 v[158:161], v[170:173], v[202:205], v[158:161]
	ds_read_b64_tr_b16 v[170:171], v242 offset:256
	ds_read_b64_tr_b16 v[172:173], v242 offset:8448
	s_waitcnt lgkmcnt(6)
	v_mfma_f32_16x16x32_bf16 v[142:145], v[174:177], v[190:193], v[142:145]
	v_mfma_f32_16x16x32_bf16 v[158:161], v[174:177], v[206:209], v[158:161]
	ds_read_b64_tr_b16 v[174:175], v242 offset:16640
	ds_read_b64_tr_b16 v[176:177], v242 offset:24832
	s_add_i32 s4, s91, 0xb0
	s_cmp_le_u32 s4, s3
	s_cbranch_scc0 .Lat_diag_b

.Lat_end_b:
.Lat_done:
	s_waitcnt lgkmcnt(0)
	s_barrier
	s_nop 1
	v_permlane16_swap_b32_e32 v232, v244
	v_add_f32_e32 v232, v232, v244
	v_mov_b32_e32 v244, v232
	s_nop 1
	v_permlane32_swap_b32_e32 v232, v244
	v_add_f32_e32 v232, v232, v244
	v_mul_f32_e32 v232, 0.5, v232
	s_sub_i32 s4, s96, 0x20200
	s_lshl_b32 s4, s4, 6
	v_and_b32_e32 v234, 15, v211
	v_lshrrev_b32_e32 v235, 4, v211
	v_xor_b32_e32 v236, v234, v235
	v_lshlrev_b32_e32 v236, 4, v236
	v_lshl_add_u32 v236, v234, 10, v236
	v_add_u32_e32 v236, s4, v236
	v_lshrrev_b32_e32 v237, 2, v217
	v_lshlrev_b32_e32 v238, 2, v218
	v_xor_b32_e32 v237, v237, v238
	v_lshlrev_b32_e32 v237, 4, v237
	v_and_b32_e32 v238, 3, v217
	v_lshl_add_u32 v237, v238, 2, v237
	v_lshl_add_u32 v237, v218, 12, v237
	v_add_u32_e32 v238, s4, v237
	v_xor_b32_e32 v239, 16, v238
	v_xor_b32_e32 v240, 32, v238
	v_xor_b32_e32 v241, 48, v238
	ds_write_b128 v236, v[114:117]
	v_xor_b32_e32 v234, 64, v236
	ds_write_b128 v234, v[118:121]
	v_xor_b32_e32 v234, 0x80, v236
	ds_write_b128 v234, v[98:101]
	v_xor_b32_e32 v234, 0xc0, v236
	ds_write_b128 v234, v[102:105]
	v_xor_b32_e32 v234, 0x100, v236
	ds_write_b128 v234, v[82:85]
	v_xor_b32_e32 v234, 0x140, v236
	ds_write_b128 v234, v[86:89]
	v_xor_b32_e32 v234, 0x180, v236
	ds_write_b128 v234, v[66:69]
	v_xor_b32_e32 v234, 0x1c0, v236
	ds_write_b128 v234, v[70:73]
	v_xor_b32_e32 v234, 0x200, v236
	ds_write_b128 v234, v[50:53]
	v_xor_b32_e32 v234, 0x240, v236
	ds_write_b128 v234, v[54:57]
	v_xor_b32_e32 v234, 0x280, v236
	ds_write_b128 v234, v[34:37]
	v_xor_b32_e32 v234, 0x2c0, v236
	ds_write_b128 v234, v[38:41]
	v_xor_b32_e32 v234, 0x300, v236
	ds_write_b128 v234, v[18:21]
	v_xor_b32_e32 v234, 0x340, v236
	ds_write_b128 v234, v[22:25]
	v_xor_b32_e32 v234, 0x380, v236
	ds_write_b128 v234, v[2:5]
	v_xor_b32_e32 v234, 0x3c0, v236
	ds_write_b128 v234, v[6:9]
	s_waitcnt lgkmcnt(0)
	ds_read_b32 v114, v238 offset:0
	ds_read_b32 v115, v239 offset:1024
	ds_read_b32 v116, v240 offset:2048
	ds_read_b32 v117, v241 offset:3072
	ds_read_b32 v118, v238 offset:8320
	ds_read_b32 v119, v239 offset:9344
	ds_read_b32 v120, v240 offset:10368
	ds_read_b32 v121, v241 offset:11392
	ds_read_b32 v98, v238 offset:128
	ds_read_b32 v99, v239 offset:1152
	ds_read_b32 v100, v240 offset:2176
	ds_read_b32 v101, v241 offset:3200
	ds_read_b32 v102, v238 offset:8192
	ds_read_b32 v103, v239 offset:9216
	ds_read_b32 v104, v240 offset:10240
	ds_read_b32 v105, v241 offset:11264
	ds_read_b32 v82, v238 offset:256
	ds_read_b32 v83, v239 offset:1280
	ds_read_b32 v84, v240 offset:2304
	ds_read_b32 v85, v241 offset:3328
	ds_read_b32 v86, v238 offset:8576
	ds_read_b32 v87, v239 offset:9600
	ds_read_b32 v88, v240 offset:10624
	ds_read_b32 v89, v241 offset:11648
	ds_read_b32 v66, v238 offset:384
	ds_read_b32 v67, v239 offset:1408
	ds_read_b32 v68, v240 offset:2432
	ds_read_b32 v69, v241 offset:3456
	ds_read_b32 v70, v238 offset:8448
	ds_read_b32 v71, v239 offset:9472
	ds_read_b32 v72, v240 offset:10496
	ds_read_b32 v73, v241 offset:11520
	ds_read_b32 v50, v238 offset:512
	ds_read_b32 v51, v239 offset:1536
	ds_read_b32 v52, v240 offset:2560
	ds_read_b32 v53, v241 offset:3584
	ds_read_b32 v54, v238 offset:8832
	ds_read_b32 v55, v239 offset:9856
	ds_read_b32 v56, v240 offset:10880
	ds_read_b32 v57, v241 offset:11904
	ds_read_b32 v34, v238 offset:640
	ds_read_b32 v35, v239 offset:1664
	ds_read_b32 v36, v240 offset:2688
	ds_read_b32 v37, v241 offset:3712
	ds_read_b32 v38, v238 offset:8704
	ds_read_b32 v39, v239 offset:9728
	ds_read_b32 v40, v240 offset:10752
	ds_read_b32 v41, v241 offset:11776
	ds_read_b32 v18, v238 offset:768
	ds_read_b32 v19, v239 offset:1792
	ds_read_b32 v20, v240 offset:2816
	ds_read_b32 v21, v241 offset:3840
	ds_read_b32 v22, v238 offset:9088
	ds_read_b32 v23, v239 offset:10112
	ds_read_b32 v24, v240 offset:11136
	ds_read_b32 v25, v241 offset:12160
	ds_read_b32 v2, v238 offset:896
	ds_read_b32 v3, v239 offset:1920
	ds_read_b32 v4, v240 offset:2944
	ds_read_b32 v5, v241 offset:3968
	ds_read_b32 v6, v238 offset:8960
	ds_read_b32 v7, v239 offset:9984
	ds_read_b32 v8, v240 offset:11008
	ds_read_b32 v9, v241 offset:12032
	s_waitcnt lgkmcnt(0)
	ds_write_b128 v236, v[122:125]
	v_xor_b32_e32 v234, 64, v236
	ds_write_b128 v234, v[126:129]
	v_xor_b32_e32 v234, 0x80, v236
	ds_write_b128 v234, v[106:109]
	v_xor_b32_e32 v234, 0xc0, v236
	ds_write_b128 v234, v[110:113]
	v_xor_b32_e32 v234, 0x100, v236
	ds_write_b128 v234, v[90:93]
	v_xor_b32_e32 v234, 0x140, v236
	ds_write_b128 v234, v[94:97]
	v_xor_b32_e32 v234, 0x180, v236
	ds_write_b128 v234, v[74:77]
	v_xor_b32_e32 v234, 0x1c0, v236
	ds_write_b128 v234, v[78:81]
	v_xor_b32_e32 v234, 0x200, v236
	ds_write_b128 v234, v[58:61]
	v_xor_b32_e32 v234, 0x240, v236
	ds_write_b128 v234, v[62:65]
	v_xor_b32_e32 v234, 0x280, v236
	ds_write_b128 v234, v[42:45]
	v_xor_b32_e32 v234, 0x2c0, v236
	ds_write_b128 v234, v[46:49]
	v_xor_b32_e32 v234, 0x300, v236
	ds_write_b128 v234, v[26:29]
	v_xor_b32_e32 v234, 0x340, v236
	ds_write_b128 v234, v[30:33]
	v_xor_b32_e32 v234, 0x380, v236
	ds_write_b128 v234, v[10:13]
	v_xor_b32_e32 v234, 0x3c0, v236
	ds_write_b128 v234, v[14:17]
	s_waitcnt lgkmcnt(0)
	ds_read_b32 v122, v238 offset:0
	ds_read_b32 v123, v239 offset:1024
	ds_read_b32 v124, v240 offset:2048
	ds_read_b32 v125, v241 offset:3072
	ds_read_b32 v126, v238 offset:8320
	ds_read_b32 v127, v239 offset:9344
	ds_read_b32 v128, v240 offset:10368
	ds_read_b32 v129, v241 offset:11392
	ds_read_b32 v106, v238 offset:128
	ds_read_b32 v107, v239 offset:1152
	ds_read_b32 v108, v240 offset:2176
	ds_read_b32 v109, v241 offset:3200
	ds_read_b32 v110, v238 offset:8192
	ds_read_b32 v111, v239 offset:9216
	ds_read_b32 v112, v240 offset:10240
	ds_read_b32 v113, v241 offset:11264
	ds_read_b32 v90, v238 offset:256
	ds_read_b32 v91, v239 offset:1280
	ds_read_b32 v92, v240 offset:2304
	ds_read_b32 v93, v241 offset:3328
	ds_read_b32 v94, v238 offset:8576
	ds_read_b32 v95, v239 offset:9600
	ds_read_b32 v96, v240 offset:10624
	ds_read_b32 v97, v241 offset:11648
	ds_read_b32 v74, v238 offset:384
	ds_read_b32 v75, v239 offset:1408
	ds_read_b32 v76, v240 offset:2432
	ds_read_b32 v77, v241 offset:3456
	ds_read_b32 v78, v238 offset:8448
	ds_read_b32 v79, v239 offset:9472
	ds_read_b32 v80, v240 offset:10496
	ds_read_b32 v81, v241 offset:11520
	ds_read_b32 v58, v238 offset:512
	ds_read_b32 v59, v239 offset:1536
	ds_read_b32 v60, v240 offset:2560
	ds_read_b32 v61, v241 offset:3584
	ds_read_b32 v62, v238 offset:8832
	ds_read_b32 v63, v239 offset:9856
	ds_read_b32 v64, v240 offset:10880
	ds_read_b32 v65, v241 offset:11904
	ds_read_b32 v42, v238 offset:640
	ds_read_b32 v43, v239 offset:1664
	ds_read_b32 v44, v240 offset:2688
	ds_read_b32 v45, v241 offset:3712
	ds_read_b32 v46, v238 offset:8704
	ds_read_b32 v47, v239 offset:9728
	ds_read_b32 v48, v240 offset:10752
	ds_read_b32 v49, v241 offset:11776
	ds_read_b32 v26, v238 offset:768
	ds_read_b32 v27, v239 offset:1792
	ds_read_b32 v28, v240 offset:2816
	ds_read_b32 v29, v241 offset:3840
	ds_read_b32 v30, v238 offset:9088
	ds_read_b32 v31, v239 offset:10112
	ds_read_b32 v32, v240 offset:11136
	ds_read_b32 v33, v241 offset:12160
	ds_read_b32 v10, v238 offset:896
	ds_read_b32 v11, v239 offset:1920
	ds_read_b32 v12, v240 offset:2944
	ds_read_b32 v13, v241 offset:3968
	ds_read_b32 v14, v238 offset:8960
	ds_read_b32 v15, v239 offset:9984
	ds_read_b32 v16, v240 offset:11008
	ds_read_b32 v17, v241 offset:12032
	s_waitcnt lgkmcnt(0)
	s_mov_b32 m0, s92
	s_branch .LBB0_353
